# merge unit-end barrier with queue item broadcast barrier (thread0 writes next item before the unit's final barrier)
# speedup vs baseline: 1.0030x; 1.0030x over previous
.Lunit_item_read:
	ds_read_b32 v2, v2
	s_xor_b32 s39, s39, 1
	v_mov_b32_e32 v236, v84
	s_waitcnt lgkmcnt(0)
	v_cmp_lt_i32_e32 vcc, s85, v2
	v_readfirstlane_b32 s10, v2
	s_cbranch_vccnz .LBB0_315

.LBB0_375:
	s_or_b64 exec, exec, s[54:55]
	s_waitcnt lgkmcnt(0)
	ds_read_b128 v[34:37], v89 offset:128
	ds_read_b128 v[38:41], v89 offset:160
	s_lshl_b64 s[0:1], s[52:53], 24
	s_add_u32 s0, s19, s0
	s_addc_u32 s1, s20, s1
	s_waitcnt lgkmcnt(1)
	v_rcp_f32_e32 v42, v34
	s_lshl_b32 s46, s46, 12
	s_add_i32 s46, s46, 0
	v_rcp_f32_e32 v43, v35
	s_add_i32 s46, s46, 0x18800
	v_lshlrev_b32_e32 v50, 1, v86
	v_lshlrev_b32_e32 v51, 9, v88
	v_mul_f32_e32 v2, v2, v42
	v_add3_u32 v50, s46, v50, v51
	v_cvt_pk_bf16_f32 v2, v2, s0
	ds_write_b16 v50, v2
	v_mul_f32_e32 v2, v18, v42
	v_cvt_pk_bf16_f32 v2, v2, s0
	v_rcp_f32_e32 v44, v36
	ds_write_b16 v50, v2 offset:64
	v_mul_f32_e32 v2, v3, v43
	v_cvt_pk_bf16_f32 v2, v2, s0
	ds_write_b16 v50, v2 offset:128
	v_mul_f32_e32 v2, v19, v43
	v_cvt_pk_bf16_f32 v2, v2, s0
	v_rcp_f32_e32 v45, v37
	ds_write_b16 v50, v2 offset:192
	v_mul_f32_e32 v2, v4, v44
	v_cvt_pk_bf16_f32 v2, v2, s0
	ds_write_b16 v50, v2 offset:256
	v_mul_f32_e32 v2, v20, v44
	v_cvt_pk_bf16_f32 v2, v2, s0
	s_waitcnt lgkmcnt(5)
	v_rcp_f32_e32 v46, v38
	ds_write_b16 v50, v2 offset:320
	v_mul_f32_e32 v2, v5, v45
	v_cvt_pk_bf16_f32 v2, v2, s0
	ds_write_b16 v50, v2 offset:384
	v_mul_f32_e32 v2, v21, v45
	v_cvt_pk_bf16_f32 v2, v2, s0
	v_rcp_f32_e32 v47, v39
	ds_write_b16 v50, v2 offset:448
	v_mul_f32_e32 v2, v6, v46
	v_cvt_pk_bf16_f32 v2, v2, s0
	ds_write_b16 v50, v2 offset:1024
	v_mul_f32_e32 v2, v22, v46
	v_cvt_pk_bf16_f32 v2, v2, s0
	v_rcp_f32_e32 v48, v40
	ds_write_b16 v50, v2 offset:1088
	v_mul_f32_e32 v2, v7, v47
	v_cvt_pk_bf16_f32 v2, v2, s0
	ds_write_b16 v50, v2 offset:1152
	v_mul_f32_e32 v2, v23, v47
	ds_read_b128 v[34:37], v89 offset:192
	v_cvt_pk_bf16_f32 v2, v2, s0
	v_rcp_f32_e32 v49, v41
	ds_write_b16 v50, v2 offset:1216
	v_mul_f32_e32 v2, v8, v48
	v_cvt_pk_bf16_f32 v2, v2, s0
	ds_write_b16 v50, v2 offset:1280
	v_mul_f32_e32 v2, v24, v48
	v_cvt_pk_bf16_f32 v2, v2, s0
	ds_read_b128 v[38:41], v89 offset:224
	s_waitcnt lgkmcnt(3)
	v_rcp_f32_e32 v34, v34
	ds_write_b16 v50, v2 offset:1344
	v_mul_f32_e32 v2, v9, v49
	v_cvt_pk_bf16_f32 v2, v2, s0
	ds_write_b16 v50, v2 offset:1408
	v_mul_f32_e32 v2, v25, v49
	v_cvt_pk_bf16_f32 v2, v2, s0
	v_rcp_f32_e32 v35, v35
	ds_write_b16 v50, v2 offset:1472
	v_mul_f32_e32 v2, v10, v34
	v_cvt_pk_bf16_f32 v2, v2, s0
	ds_write_b16 v50, v2 offset:2048
	v_mul_f32_e32 v2, v26, v34
	v_cvt_pk_bf16_f32 v2, v2, s0
	v_rcp_f32_e32 v36, v36
	ds_write_b16 v50, v2 offset:2112
	v_mul_f32_e32 v2, v11, v35
	v_cvt_pk_bf16_f32 v2, v2, s0
	ds_write_b16 v50, v2 offset:2176
	v_mul_f32_e32 v2, v27, v35
	v_cvt_pk_bf16_f32 v2, v2, s0
	v_rcp_f32_e32 v37, v37
	ds_write_b16 v50, v2 offset:2240
	v_mul_f32_e32 v2, v12, v36
	v_cvt_pk_bf16_f32 v2, v2, s0
	ds_write_b16 v50, v2 offset:2304
	v_mul_f32_e32 v2, v28, v36
	v_cvt_pk_bf16_f32 v2, v2, s0
	s_waitcnt lgkmcnt(8)
	v_rcp_f32_e32 v38, v38
	ds_write_b16 v50, v2 offset:2368
	v_mul_f32_e32 v2, v13, v37
	v_cvt_pk_bf16_f32 v2, v2, s0
	ds_write_b16 v50, v2 offset:2432
	v_mul_f32_e32 v2, v29, v37
	v_cvt_pk_bf16_f32 v2, v2, s0
	v_rcp_f32_e32 v39, v39
	ds_write_b16 v50, v2 offset:2496
	v_mul_f32_e32 v2, v14, v38
	v_cvt_pk_bf16_f32 v2, v2, s0
	ds_write_b16 v50, v2 offset:3072
	v_mul_f32_e32 v2, v30, v38
	v_cvt_pk_bf16_f32 v2, v2, s0
	v_rcp_f32_e32 v40, v40
	ds_write_b16 v50, v2 offset:3136
	v_mul_f32_e32 v2, v15, v39
	v_cvt_pk_bf16_f32 v2, v2, s0
	ds_write_b16 v50, v2 offset:3200
	v_mul_f32_e32 v2, v31, v39
	v_cvt_pk_bf16_f32 v2, v2, s0
	v_rcp_f32_e32 v41, v41
	ds_write_b16 v50, v2 offset:3264
	v_mul_f32_e32 v2, v16, v40
	v_cvt_pk_bf16_f32 v2, v2, s0
	ds_write_b16 v50, v2 offset:3328
	v_mul_f32_e32 v2, v32, v40
	v_cvt_pk_bf16_f32 v2, v2, s0
	ds_write_b16 v50, v2 offset:3392
	v_mul_f32_e32 v2, v17, v41
	v_cvt_pk_bf16_f32 v2, v2, s0
	ds_write_b16 v50, v2 offset:3456
	v_mul_f32_e32 v2, v33, v41
	v_cvt_pk_bf16_f32 v2, v2, s0
	ds_write_b16 v50, v2 offset:3520
	v_lshlrev_b32_e32 v2, 1, v87
	v_and_b32_e32 v206, 0x70, v2
	v_lshrrev_b32_e32 v14, 3, v85
	v_add_u32_e32 v15, s46, v206
	s_add_i32 s48, s48, s45
	s_waitcnt lgkmcnt(0)
	v_lshl_add_u32 v2, v14, 7, v15
	v_or_b32_e32 v6, s48, v14
	ds_read_b128 v[2:5], v2
	v_ashrrev_i32_e32 v7, 31, v6
	s_add_u32 s0, s0, s30
	v_lshlrev_b64 v[6:7], s44, v[6:7]
	s_addc_u32 s1, s1, s31
	v_lshl_add_u64 v[6:7], v[6:7], 0, s[28:29]
	v_lshl_add_u64 v[10:11], s[0:1], 0, v[206:207]
	v_lshlrev_b64 v[6:7], 10, v[6:7]
	v_or_b32_e32 v16, 8, v14
	v_lshl_add_u64 v[12:13], v[10:11], 0, v[6:7]
	v_lshl_add_u32 v6, v16, 7, v15
	ds_read_b128 v[6:9], v6
	s_waitcnt lgkmcnt(1)
	global_store_dwordx4 v[12:13], v[2:5], off sc1
	s_nop 1
	v_or_b32_e32 v2, s48, v16
	v_ashrrev_i32_e32 v3, 31, v2
	v_lshlrev_b64 v[2:3], s44, v[2:3]
	v_lshl_add_u64 v[2:3], v[2:3], 0, s[28:29]
	v_lshlrev_b64 v[2:3], 10, v[2:3]
	v_lshl_add_u64 v[2:3], v[10:11], 0, v[2:3]
	s_waitcnt lgkmcnt(0)
	global_store_dwordx4 v[2:3], v[6:9], off sc1
	s_nop 1
	v_or_b32_e32 v6, 16, v14
	v_lshl_add_u32 v2, v6, 7, v15
	v_or_b32_e32 v6, s48, v6
	ds_read_b128 v[2:5], v2
	v_ashrrev_i32_e32 v7, 31, v6
	v_lshlrev_b64 v[6:7], s44, v[6:7]
	v_lshl_add_u64 v[6:7], v[6:7], 0, s[28:29]
	v_lshlrev_b64 v[6:7], 10, v[6:7]
	v_or_b32_e32 v14, 24, v14
	v_lshl_add_u64 v[12:13], v[10:11], 0, v[6:7]
	v_lshl_add_u32 v6, v14, 7, v15
	ds_read_b128 v[6:9], v6
	s_waitcnt lgkmcnt(1)
	global_store_dwordx4 v[12:13], v[2:5], off sc1
	s_nop 1
	v_or_b32_e32 v2, s48, v14
	v_ashrrev_i32_e32 v3, 31, v2
	v_lshlrev_b64 v[2:3], s44, v[2:3]
	v_lshl_add_u64 v[2:3], v[2:3], 0, s[28:29]
	v_lshlrev_b64 v[2:3], 10, v[2:3]
	v_lshl_add_u64 v[2:3], v[10:11], 0, v[2:3]
	s_waitcnt lgkmcnt(0)
	global_store_dwordx4 v[2:3], v[6:9], off sc1
	s_and_saveexec_b64 s[0:1], s[14:15]
	s_cbranch_execz .Ldil_end_skip
	s_lshl_b32 s6, s39, 2
	s_add_i32 s6, s6, 0x22188
	v_mov_b32_e32 v2, s6
	ds_write_b32 v2, v252
.Ldil_end_skip:
	s_or_b64 exec, exec, s[0:1]
	s_lshl_b32 s0, s39, 2
	s_add_i32 s0, s0, 0x22188
	v_mov_b32_e32 v2, s0
	s_waitcnt lgkmcnt(0)
	s_barrier
	s_branch .Lunit_item_read

.LBB0_384:
	v_add_f32_e32 v35, v52, v53
	v_add_f32_e32 v35, v54, v35
	v_add_f32_e32 v35, v55, v35
	v_add_f32_e32 v35, v56, v35
	v_add_f32_e32 v35, v57, v35
	v_add_f32_e32 v35, v58, v35
	v_add_f32_e32 v35, v59, v35
	v_add_f32_e32 v35, v60, v35
	v_add_f32_e32 v35, v61, v35
	v_add_f32_e32 v35, v62, v35
	v_add_f32_e32 v35, v63, v35
	v_add_f32_e32 v35, v64, v35
	v_add_f32_e32 v35, v65, v35
	v_add_f32_e32 v35, v66, v35
	v_add_f32_e32 v35, v67, v35
	v_add_f32_e32 v35, v36, v35
	v_add_f32_e32 v35, v37, v35
	v_add_f32_e32 v35, v38, v35
	v_add_f32_e32 v35, v39, v35
	v_add_f32_e32 v35, v40, v35
	v_add_f32_e32 v35, v41, v35
	v_add_f32_e32 v35, v42, v35
	v_add_f32_e32 v35, v43, v35
	v_add_f32_e32 v35, v44, v35
	v_add_f32_e32 v35, v45, v35
	v_add_f32_e32 v35, v46, v35
	v_add_f32_e32 v35, v47, v35
	v_add_f32_e32 v35, v48, v35
	v_add_f32_e32 v35, v49, v35
	s_cmp_lg_u32 0, -1
	v_add_f32_e32 v35, v50, v35
	s_cselect_b32 s0, 0, 0
	v_add_f32_e32 v35, v51, v35
	s_addk_i32 s0, 0x6000
	v_pk_mul_f32 v[32:33], v[210:211], v[32:33] op_sel_hi:[0,1]
	v_pk_mul_f32 v[30:31], v[210:211], v[30:31] op_sel_hi:[0,1]
	v_pk_mul_f32 v[28:29], v[210:211], v[28:29] op_sel_hi:[0,1]
	v_pk_mul_f32 v[26:27], v[210:211], v[26:27] op_sel_hi:[0,1]
	v_pk_mul_f32 v[24:25], v[210:211], v[24:25] op_sel_hi:[0,1]
	v_pk_mul_f32 v[22:23], v[210:211], v[22:23] op_sel_hi:[0,1]
	v_pk_mul_f32 v[20:21], v[210:211], v[20:21] op_sel_hi:[0,1]
	v_pk_mul_f32 v[18:19], v[210:211], v[18:19] op_sel_hi:[0,1]
	v_pk_mul_f32 v[16:17], v[210:211], v[16:17] op_sel_hi:[0,1]
	v_pk_mul_f32 v[14:15], v[210:211], v[14:15] op_sel_hi:[0,1]
	v_pk_mul_f32 v[12:13], v[210:211], v[12:13] op_sel_hi:[0,1]
	v_pk_mul_f32 v[10:11], v[210:211], v[10:11] op_sel_hi:[0,1]
	v_pk_mul_f32 v[8:9], v[210:211], v[8:9] op_sel_hi:[0,1]
	v_pk_mul_f32 v[6:7], v[210:211], v[6:7] op_sel_hi:[0,1]
	v_pk_mul_f32 v[4:5], v[210:211], v[4:5] op_sel_hi:[0,1]
	v_pk_mul_f32 v[2:3], v[210:211], v[2:3] op_sel_hi:[0,1]
	v_fmac_f32_e32 v35, v210, v34
	v_add3_u32 v68, v244, s0, v240
	v_cvt_pk_bf16_f32 v52, v52, v53
	v_cvt_pk_bf16_f32 v53, v54, v55
	v_cvt_pk_bf16_f32 v54, v56, v57
	v_cvt_pk_bf16_f32 v55, v58, v59
	v_cvt_pk_bf16_f32 v56, v60, v61
	v_cvt_pk_bf16_f32 v57, v62, v63
	v_cvt_pk_bf16_f32 v58, v64, v65
	v_cvt_pk_bf16_f32 v59, v66, v67
	v_cvt_pk_bf16_f32 v36, v36, v37
	v_cvt_pk_bf16_f32 v37, v38, v39
	v_cvt_pk_bf16_f32 v38, v40, v41
	v_cvt_pk_bf16_f32 v39, v42, v43
	v_cvt_pk_bf16_f32 v40, v44, v45
	v_cvt_pk_bf16_f32 v41, v46, v47
	v_cvt_pk_bf16_f32 v42, v48, v49
	v_cvt_pk_bf16_f32 v43, v50, v51
	v_add3_u32 v34, v68, v241, s46
	ds_read_b64_tr_b16 v[44:45],v34 offset:0
	ds_read_b64_tr_b16 v[46:47],v34 offset:512
	ds_read_b64_tr_b16 v[48:49],v34 offset:1024
	ds_read_b64_tr_b16 v[50:51],v34 offset:1536
	ds_read_b64_tr_b16 v[60:61],v34 offset:2048
	ds_read_b64_tr_b16 v[62:63],v34 offset:2560
	ds_read_b64_tr_b16 v[64:65],v34 offset:3072
	ds_read_b64_tr_b16 v[66:67],v34 offset:3584
	s_waitcnt lgkmcnt(0)
	s_nop 0
	v_mfma_f32_32x32x16_bf16 v[2:17], v[52:55], v[44:47], v[2:17]
	ds_read_b64_tr_b16 v[44:45],v34 offset:4096
	ds_read_b64_tr_b16 v[46:47],v34 offset:4608
	v_mfma_f32_32x32x16_bf16 v[2:17], v[56:59], v[48:51], v[2:17]
	ds_read_b64_tr_b16 v[48:49],v34 offset:5120
	ds_read_b64_tr_b16 v[50:51],v34 offset:5632
	v_mfma_f32_32x32x16_bf16 v[2:17], v[36:39], v[60:63], v[2:17]
	ds_read_b64_tr_b16 v[60:61],v34 offset:6144
	ds_read_b64_tr_b16 v[62:63],v34 offset:6656
	v_mfma_f32_32x32x16_bf16 v[2:17], v[40:43], v[64:67], v[2:17]
	ds_read_b64_tr_b16 v[64:65],v34 offset:7168
	ds_read_b64_tr_b16 v[66:67],v34 offset:7680
	s_waitcnt lgkmcnt(0)
	v_mfma_f32_32x32x16_bf16 v[18:33], v[52:55], v[44:47], v[18:33]
	v_mov_b32_e32 v34, v35
	s_nop 1
	v_permlane32_swap_b32_e32 v35, v34
	v_cmp_gt_u32_e32 vcc, 32, v209
	v_mfma_f32_32x32x16_bf16 v[18:33], v[56:59], v[48:51], v[18:33]
	v_mfma_f32_32x32x16_bf16 v[18:33], v[36:39], v[60:63], v[18:33]
	v_mfma_f32_32x32x16_bf16 v[18:33], v[40:43], v[64:67], v[18:33]
	s_and_saveexec_b64 s[0:1], vcc
	v_add_f32_e32 v34, v35, v34
	ds_write_b32 v243, v34 offset:49280
	s_or_b64 exec, exec, s[0:1]
	s_waitcnt lgkmcnt(0)
	ds_read_b128 v[34:37], v242 offset:49280
	ds_read_b128 v[38:41], v242 offset:49312
	s_lshl_b32 s0, s43, 12
	s_add_i32 s6, s0, 0
	v_lshlrev_b32_e32 v50, 1, v238
	s_waitcnt lgkmcnt(1)
	v_rcp_f32_e32 v42, v34
	v_rcp_f32_e32 v43, v35
	v_lshlrev_b32_e32 v51, 9, v239
	v_add3_u32 v50, s6, v50, v51
	v_mul_f32_e32 v2, v2, v42
	v_cvt_pk_bf16_f32 v2, v2, s0
	v_rcp_f32_e32 v44, v36
	v_rcp_f32_e32 v45, v37
	s_waitcnt lgkmcnt(0)
	v_rcp_f32_e32 v46, v38
	ds_read_b128 v[34:37], v242 offset:49344
	v_rcp_f32_e32 v47, v39
	v_rcp_f32_e32 v48, v40
	v_rcp_f32_e32 v49, v41
	ds_read_b128 v[38:41], v242 offset:49376
	ds_write_b16 v50, v2 offset:51200
	v_mul_f32_e32 v2, v18, v42
	v_cvt_pk_bf16_f32 v2, v2, s0
	ds_write_b16 v50, v2 offset:51264
	v_mul_f32_e32 v2, v3, v43
	v_cvt_pk_bf16_f32 v2, v2, s0
	ds_write_b16 v50, v2 offset:51328
	v_mul_f32_e32 v2, v19, v43
	v_cvt_pk_bf16_f32 v2, v2, s0
	ds_write_b16 v50, v2 offset:51392
	v_mul_f32_e32 v2, v4, v44
	v_cvt_pk_bf16_f32 v2, v2, s0
	ds_write_b16 v50, v2 offset:51456
	v_mul_f32_e32 v2, v20, v44
	v_cvt_pk_bf16_f32 v2, v2, s0
	ds_write_b16 v50, v2 offset:51520
	v_mul_f32_e32 v2, v5, v45
	v_cvt_pk_bf16_f32 v2, v2, s0
	ds_write_b16 v50, v2 offset:51584
	v_mul_f32_e32 v2, v21, v45
	v_cvt_pk_bf16_f32 v2, v2, s0
	ds_write_b16 v50, v2 offset:51648
	v_mul_f32_e32 v2, v6, v46
	v_cvt_pk_bf16_f32 v2, v2, s0
	ds_write_b16 v50, v2 offset:52224
	v_mul_f32_e32 v2, v22, v46
	v_cvt_pk_bf16_f32 v2, v2, s0
	ds_write_b16 v50, v2 offset:52288
	v_mul_f32_e32 v2, v7, v47
	v_cvt_pk_bf16_f32 v2, v2, s0
	ds_write_b16 v50, v2 offset:52352
	v_mul_f32_e32 v2, v23, v47
	v_cvt_pk_bf16_f32 v2, v2, s0
	ds_write_b16 v50, v2 offset:52416
	v_mul_f32_e32 v2, v8, v48
	v_cvt_pk_bf16_f32 v2, v2, s0
	ds_write_b16 v50, v2 offset:52480
	v_mul_f32_e32 v2, v24, v48
	v_cvt_pk_bf16_f32 v2, v2, s0
	s_waitcnt lgkmcnt(14)
	v_rcp_f32_e32 v34, v34
	ds_write_b16 v50, v2 offset:52544
	v_mul_f32_e32 v2, v9, v49
	v_cvt_pk_bf16_f32 v2, v2, s0
	ds_write_b16 v50, v2 offset:52608
	v_mul_f32_e32 v2, v25, v49
	v_cvt_pk_bf16_f32 v2, v2, s0
	v_rcp_f32_e32 v35, v35
	ds_write_b16 v50, v2 offset:52672
	v_mul_f32_e32 v2, v10, v34
	v_cvt_pk_bf16_f32 v2, v2, s0
	ds_write_b16 v50, v2 offset:53248
	v_mul_f32_e32 v2, v26, v34
	v_cvt_pk_bf16_f32 v2, v2, s0
	v_rcp_f32_e32 v36, v36
	ds_write_b16 v50, v2 offset:53312
	v_mul_f32_e32 v2, v11, v35
	v_cvt_pk_bf16_f32 v2, v2, s0
	ds_write_b16 v50, v2 offset:53376
	v_mul_f32_e32 v2, v27, v35
	v_cvt_pk_bf16_f32 v2, v2, s0
	v_rcp_f32_e32 v37, v37
	ds_write_b16 v50, v2 offset:53440
	v_mul_f32_e32 v2, v12, v36
	v_cvt_pk_bf16_f32 v2, v2, s0
	ds_write_b16 v50, v2 offset:53504
	v_mul_f32_e32 v2, v28, v36
	v_cvt_pk_bf16_f32 v2, v2, s0
	s_waitcnt lgkmcnt(14)
	v_rcp_f32_e32 v38, v38
	ds_write_b16 v50, v2 offset:53568
	v_mul_f32_e32 v2, v13, v37
	v_cvt_pk_bf16_f32 v2, v2, s0
	ds_write_b16 v50, v2 offset:53632
	v_mul_f32_e32 v2, v29, v37
	v_cvt_pk_bf16_f32 v2, v2, s0
	v_rcp_f32_e32 v39, v39
	ds_write_b16 v50, v2 offset:53696
	v_mul_f32_e32 v2, v14, v38
	v_cvt_pk_bf16_f32 v2, v2, s0
	ds_write_b16 v50, v2 offset:54272
	v_mul_f32_e32 v2, v30, v38
	v_cvt_pk_bf16_f32 v2, v2, s0
	v_rcp_f32_e32 v40, v40
	ds_write_b16 v50, v2 offset:54336
	v_mul_f32_e32 v2, v15, v39
	v_cvt_pk_bf16_f32 v2, v2, s0
	ds_write_b16 v50, v2 offset:54400
	v_mul_f32_e32 v2, v31, v39
	v_cvt_pk_bf16_f32 v2, v2, s0
	v_rcp_f32_e32 v41, v41
	ds_write_b16 v50, v2 offset:54464
	v_mul_f32_e32 v2, v16, v40
	v_cvt_pk_bf16_f32 v2, v2, s0
	ds_write_b16 v50, v2 offset:54528
	v_mul_f32_e32 v2, v32, v40
	v_cvt_pk_bf16_f32 v2, v2, s0
	ds_write_b16 v50, v2 offset:54592
	v_mul_f32_e32 v2, v17, v41
	v_cvt_pk_bf16_f32 v2, v2, s0
	ds_write_b16 v50, v2 offset:54656
	v_mul_f32_e32 v2, v33, v41
	v_cvt_pk_bf16_f32 v2, v2, s0
	ds_write_b16 v50, v2 offset:54720
	v_lshlrev_b32_e32 v2, 1, v237
	v_and_b32_e32 v206, 0x70, v2
	s_ashr_i32 s29, s28, 31
	s_lshl_b64 s[0:1], s[30:31], 1
	v_lshrrev_b32_e32 v14, 3, v209
	v_add_u32_e32 v15, s6, v206
	s_add_u32 s7, s56, s0
	s_waitcnt lgkmcnt(0)
	v_lshl_add_u32 v2, v14, 7, v15
	v_or_b32_e32 v16, 8, v14
	s_addc_u32 s10, s57, s1
	s_lshl_b64 s[0:1], s[28:29], 1
	ds_read_b128 v[2:5], v2 offset:51200
	v_lshl_add_u32 v6, v16, 7, v15
	s_add_u32 s0, s7, s0
	ds_read_b128 v[6:9], v6 offset:51200
	s_addc_u32 s1, s10, s1
	v_lshl_add_u64 v[10:11], s[0:1], 0, v[206:207]
	v_lshlrev_b32_e32 v206, 11, v14
	v_lshl_add_u64 v[12:13], v[10:11], 0, v[206:207]
	v_lshlrev_b32_e32 v206, 11, v16
	s_waitcnt lgkmcnt(1)
	global_store_dwordx4 v[12:13], v[2:5], off sc1
	v_mov_b32_e32 v84, v236
	s_nop 0
	v_lshl_add_u64 v[2:3], v[10:11], 0, v[206:207]
	s_waitcnt lgkmcnt(0)
	global_store_dwordx4 v[2:3], v[6:9], off sc1
	s_nop 1
	v_or_b32_e32 v6, 16, v14
	v_lshl_add_u32 v2, v6, 7, v15
	v_or_b32_e32 v14, 24, v14
	ds_read_b128 v[2:5], v2 offset:51200
	v_lshlrev_b32_e32 v206, 11, v6
	v_lshl_add_u32 v6, v14, 7, v15
	ds_read_b128 v[6:9], v6 offset:51200
	v_lshl_add_u64 v[12:13], v[10:11], 0, v[206:207]
	v_lshlrev_b32_e32 v206, 11, v14
	s_waitcnt lgkmcnt(1)
	global_store_dwordx4 v[12:13], v[2:5], off sc1
	s_nop 1
	v_lshl_add_u64 v[2:3], v[10:11], 0, v[206:207]
	s_waitcnt lgkmcnt(0)
	global_store_dwordx4 v[2:3], v[6:9], off sc1
	s_and_saveexec_b64 s[0:1], s[14:15]
	s_cbranch_execz .Latt_end_skip
	s_lshl_b32 s6, s39, 2
	s_add_i32 s6, s6, 0x22188
	v_mov_b32_e32 v2, s6
	ds_write_b32 v2, v252
